# v34 + MLA step loop: stage-address set-up hoisted above the step barrier, K/V pointer advances moved into the mid-step DMA block (shorter barrier-to-MFMA head and MFMA-to-barrier tail)
# speedup vs baseline: 1.0080x; 1.0080x over previous
.LBB0_784:
	s_waitcnt vmcnt(0)
	s_add_i32 s5, s2, 1
	s_cmp_eq_u32 s2, 33
	s_bitcmp1_b32 s2, 0
	s_cselect_b32 s2, 0xa000, 0
	v_add_u32_e32 v96, s2, v95
	s_waitcnt vmcnt(0) lgkmcnt(0)
	s_barrier
.LBB0_786:
	ds_read_b128 v[172:175], v96
	ds_read_b128 v[176:179], v96 offset:1024
	ds_read_b128 v[188:191], v96 offset:2048
	ds_read_b128 v[192:195], v96 offset:3072
	ds_read_b128 v[198:201], v96 offset:4096
	ds_read_b128 v[202:205], v96 offset:5120
	s_cmp_eq_u32 s5, 1
	s_cbranch_scc1 .Lmy_first
	s_waitcnt lgkmcnt(5)
	v_mfma_f32_32x32x16_bf16 v[64:79], v[172:175], v[82:85], 0
	ds_read_b128 v[172:175], v96 offset:6144
	v_max_f32_e32 v111, v218, v219
	v_max3_f32 v111, v111, v220, v221
	v_max3_f32 v111, v111, v222, v223
	v_max3_f32 v111, v111, v224, v225
	s_waitcnt lgkmcnt(5)
	v_mfma_f32_32x32x16_bf16 v[64:79], v[176:179], v[86:89], v[64:79]
	ds_read_b128 v[176:179], v96 offset:7168
	v_max3_f32 v111, v111, v226, v227
	v_max3_f32 v111, v111, v228, v229
	v_max3_f32 v111, v111, v230, v231
	v_max3_f32 v111, v111, v232, v233
	s_waitcnt lgkmcnt(5)
	v_mfma_f32_32x32x16_bf16 v[64:79], v[188:191], v[90:93], v[64:79]
	ds_read_b128 v[188:191], v96 offset:8192
	v_mul_f32_e32 v159, 0x3dd53b94, v111
	v_cmp_le_f32_e32 vcc, v159, v110
	s_cmp_eq_u64 vcc, exec
	s_cbranch_scc1 .LBB0_790
	v_mov_b32_e32 v159, v111
	s_nop 1
	v_permlane32_swap_b32_e32 v111, v159
	v_max_f32_e32 v111, v111, v159
	v_mul_f32_e32 v111, 0x3dd53b94, v111
	v_max_f32_e32 v110, v111, v111
	v_max_f32_e32 v111, v80, v80
	v_max_f32_e32 v111, v111, v110
	v_sub_f32_e32 v80, v80, v111
	v_exp_f32_e32 v80, v80
	v_xor_b32_e32 v110, 0x80000000, v111
	v_mul_f32_e32 v81, v81, v80
	v_pk_mul_f32 v[62:63], v[62:63], v[80:81] op_sel_hi:[1,0]
	v_pk_mul_f32 v[60:61], v[60:61], v[80:81] op_sel_hi:[1,0]
	v_pk_mul_f32 v[58:59], v[58:59], v[80:81] op_sel_hi:[1,0]
	v_pk_mul_f32 v[56:57], v[56:57], v[80:81] op_sel_hi:[1,0]
	v_pk_mul_f32 v[54:55], v[54:55], v[80:81] op_sel_hi:[1,0]
	v_pk_mul_f32 v[52:53], v[52:53], v[80:81] op_sel_hi:[1,0]
	v_pk_mul_f32 v[50:51], v[50:51], v[80:81] op_sel_hi:[1,0]
	v_pk_mul_f32 v[48:49], v[48:49], v[80:81] op_sel_hi:[1,0]
	v_pk_mul_f32 v[46:47], v[46:47], v[80:81] op_sel_hi:[1,0]
	v_pk_mul_f32 v[44:45], v[44:45], v[80:81] op_sel_hi:[1,0]
	v_pk_mul_f32 v[42:43], v[42:43], v[80:81] op_sel_hi:[1,0]
	v_pk_mul_f32 v[40:41], v[40:41], v[80:81] op_sel_hi:[1,0]
	v_pk_mul_f32 v[38:39], v[38:39], v[80:81] op_sel_hi:[1,0]
	v_pk_mul_f32 v[36:37], v[36:37], v[80:81] op_sel_hi:[1,0]
	v_pk_mul_f32 v[34:35], v[34:35], v[80:81] op_sel_hi:[1,0]
	v_pk_mul_f32 v[32:33], v[32:33], v[80:81] op_sel_hi:[1,0]
	v_pk_mul_f32 v[30:31], v[30:31], v[80:81] op_sel_hi:[1,0]
	v_pk_mul_f32 v[28:29], v[28:29], v[80:81] op_sel_hi:[1,0]
	v_pk_mul_f32 v[26:27], v[26:27], v[80:81] op_sel_hi:[1,0]
	v_pk_mul_f32 v[24:25], v[24:25], v[80:81] op_sel_hi:[1,0]
	v_pk_mul_f32 v[22:23], v[22:23], v[80:81] op_sel_hi:[1,0]
	v_pk_mul_f32 v[20:21], v[20:21], v[80:81] op_sel_hi:[1,0]
	v_pk_mul_f32 v[18:19], v[18:19], v[80:81] op_sel_hi:[1,0]
	v_pk_mul_f32 v[16:17], v[16:17], v[80:81] op_sel_hi:[1,0]
	v_pk_mul_f32 v[14:15], v[14:15], v[80:81] op_sel_hi:[1,0]
	v_pk_mul_f32 v[12:13], v[12:13], v[80:81] op_sel_hi:[1,0]
	v_pk_mul_f32 v[10:11], v[10:11], v[80:81] op_sel_hi:[1,0]
	v_pk_mul_f32 v[8:9], v[8:9], v[80:81] op_sel_hi:[1,0]
	v_pk_mul_f32 v[6:7], v[6:7], v[80:81] op_sel_hi:[1,0]
	v_pk_mul_f32 v[4:5], v[4:5], v[80:81] op_sel_hi:[1,0]
	v_pk_mul_f32 v[2:3], v[2:3], v[80:81] op_sel_hi:[1,0]
	v_pk_mul_f32 v[0:1], v[0:1], v[80:81] op_sel_hi:[1,0]
	v_mov_b32_e32 v80, v111
	s_branch .LBB0_791

.Lmy_join:
	s_cmp_eq_u32 s5, 34
	s_cbranch_scc1 .Lmy_nodma
	s_bitcmp1_b32 s5, 0
	s_cselect_b32 s3, 0xa000, 0
	v_lshl_add_u64 v[180:181], v[162:163], 0, s[94:95]
	s_mov_b64 s[6:7], 0x27706000
	s_add_i32 s3, s3, 0
	v_lshl_add_u64 v[214:215], v[180:181], 0, s[6:7]
	s_add_i32 s8, s3, s94
	s_mov_b32 m0, s8
	s_mov_b64 s[6:7], 0x27708000
	global_load_lds_dwordx4 v[214:215], off
	v_lshl_add_u64 v[214:215], v[180:181], 0, s[6:7]
	s_add_i32 m0, s3, s64
	s_mov_b64 s[6:7], 0x2770a000
	global_load_lds_dwordx4 v[214:215], off
	v_lshl_add_u64 v[180:181], v[180:181], 0, s[6:7]
	s_add_i32 m0, s3, s65
	s_nop 0
	global_load_lds_dwordx4 v[180:181], off
	v_lshl_add_u64 v[180:181], v[160:161], 0, s[94:95]
	s_mov_b64 s[6:7], 0x28404000
	v_lshl_add_u64 v[214:215], v[180:181], 0, s[6:7]
	s_add_i32 m0, s8, 0x3000
	s_mov_b64 s[6:7], 0x28406000
	global_load_lds_dwordx4 v[214:215], off
	v_lshl_add_u64 v[180:181], v[180:181], 0, s[6:7]
	s_add_i32 m0, s8, 0x8000
	s_nop 0
	global_load_lds_dwordx4 v[180:181], off
	v_lshl_add_u64 v[160:161], v[160:161], 0, s[26:27]
	v_lshl_add_u64 v[162:163], v[162:163], 0, s[28:29]

.LBB0_788:
	s_waitcnt lgkmcnt(9)
	v_mfma_f32_32x32x16_bf16 v[218:233], v[192:195], v[112:115], v[218:233]
	ds_read_b128 v[192:195], v96 offset:29696
	v_fma_f32 v64, v64, s80, -v80
	v_fma_f32 v65, v65, s80, -v80
	v_exp_f32_e32 v64, v64
	v_fma_f32 v66, v66, s80, -v80
	v_exp_f32_e32 v65, v65
	s_waitcnt lgkmcnt(9)
	v_mfma_f32_32x32x16_bf16 v[218:233], v[198:201], v[116:119], v[218:233]
	ds_read_b128 v[198:201], v96 offset:30720
	v_add_f32_e32 v183, 0, v64
	v_fma_f32 v67, v67, s80, -v80
	v_exp_f32_e32 v66, v66
	v_add_f32_e32 v183, v65, v183
	v_fma_f32 v68, v68, s80, -v80
	s_waitcnt lgkmcnt(9)
	v_mfma_f32_32x32x16_bf16 v[218:233], v[202:205], v[120:123], v[218:233]
	ds_read_b128 v[202:205], v96 offset:31744
	v_exp_f32_e32 v67, v67
	v_add_f32_e32 v183, v66, v183
	v_fma_f32 v69, v69, s80, -v80
	v_exp_f32_e32 v68, v68
	v_add_f32_e32 v183, v67, v183
	s_waitcnt lgkmcnt(5)
	v_mfma_f32_32x32x16_bf16 v[218:233], v[172:175], v[124:127], v[218:233]
	v_fma_f32 v70, v70, s80, -v80
	v_exp_f32_e32 v69, v69
	v_add_f32_e32 v183, v68, v183
	v_fma_f32 v71, v71, s80, -v80
	v_exp_f32_e32 v70, v70
	s_waitcnt lgkmcnt(4)
	v_mfma_f32_32x32x16_bf16 v[218:233], v[176:179], v[128:131], v[218:233]
	v_add_f32_e32 v183, v69, v183
	v_exp_f32_e32 v71, v71
	v_add_f32_e32 v183, v70, v183
	v_add_f32_e32 v183, v71, v183
	v_fma_f32 v159, v72, s80, -v80
	s_waitcnt lgkmcnt(3)
	v_mfma_f32_32x32x16_bf16 v[218:233], v[188:191], v[132:135], v[218:233]
	v_fma_f32 v111, v73, s80, -v80
	v_fma_f32 v165, v74, s80, -v80
	v_fma_f32 v166, v75, s80, -v80
	v_cvt_pk_bf16_f32 v64, v64, v65
	v_cvt_pk_bf16_f32 v65, v66, v67
	s_waitcnt lgkmcnt(2)
	v_mfma_f32_32x32x16_bf16 v[218:233], v[192:195], v[136:139], v[218:233]
	v_fma_f32 v167, v76, s80, -v80
	v_fma_f32 v168, v77, s80, -v80
	v_fma_f32 v169, v78, s80, -v80
	v_fma_f32 v170, v79, s80, -v80
	v_cvt_pk_bf16_f32 v66, v68, v69
	s_waitcnt lgkmcnt(1)
	v_mfma_f32_32x32x16_bf16 v[218:233], v[198:201], v[140:143], v[218:233]
	v_cvt_pk_bf16_f32 v67, v70, v71
	v_exp_f32_e32 v159, v159
	v_exp_f32_e32 v111, v111
	s_waitcnt lgkmcnt(0)
	v_mfma_f32_32x32x16_bf16 v[218:233], v[202:205], v[144:147], v[218:233]
	s_waitcnt lgkmcnt(9)
	v_mfma_f32_32x32x16_bf16 v[48:63], v[148:151], v[64:67], v[48:63]
	ds_read_b128 v[234:237], v96 offset:16384
	ds_read_b128 v[68:71], v96 offset:17408
	ds_read_b128 v[72:75], v96 offset:18432
	ds_read_b128 v[76:79], v96 offset:19456
	ds_read_b128 v[148:151], v96 offset:32768
	v_exp_f32_e32 v165, v165
	v_exp_f32_e32 v166, v166
	v_exp_f32_e32 v167, v167
	s_waitcnt lgkmcnt(13)
	v_mfma_f32_32x32x16_bf16 v[32:47], v[106:109], v[64:67], v[32:47]
	ds_read_b128 v[106:109], v96 offset:33792
	v_exp_f32_e32 v168, v168
	v_exp_f32_e32 v169, v169
	v_exp_f32_e32 v170, v170
	s_waitcnt lgkmcnt(12)
	v_mfma_f32_32x32x16_bf16 v[16:31], v[98:101], v[64:67], v[16:31]
	v_cvt_pk_bf16_f32 v98, v159, v111
	v_cvt_pk_bf16_f32 v99, v165, v166
	v_cvt_pk_bf16_f32 v100, v167, v168
	v_cvt_pk_bf16_f32 v101, v169, v170
	s_waitcnt lgkmcnt(13)
	v_mfma_f32_32x32x16_bf16 v[0:15], v[102:105], v[64:67], v[0:15]
	ds_read_b128 v[102:105], v96 offset:35840
	ds_read_b128 v[206:209], v96 offset:37888
	ds_read_b128 v[238:241], v96 offset:38912
	ds_read_b128 v[242:245], v96 offset:39936
	v_add_f32_e32 v183, v159, v183
	v_add_f32_e32 v183, v111, v183
	v_add_f32_e32 v183, v165, v183
	s_waitcnt lgkmcnt(9)
	v_mfma_f32_32x32x16_bf16 v[48:63], v[234:237], v[98:101], v[48:63]
	ds_read_b128 v[234:237], v96 offset:36864
	v_add_f32_e32 v183, v166, v183
	v_add_f32_e32 v183, v167, v183
	v_add_f32_e32 v183, v168, v183
	s_waitcnt lgkmcnt(9)
	v_mfma_f32_32x32x16_bf16 v[32:47], v[68:71], v[98:101], v[32:47]
	v_add_f32_e32 v183, v169, v183
	v_add_f32_e32 v183, v170, v183
	s_waitcnt lgkmcnt(8)
	v_mfma_f32_32x32x16_bf16 v[16:31], v[72:75], v[98:101], v[16:31]
	v_add_f32_e32 v81, v81, v183
	s_waitcnt lgkmcnt(7)
	v_mfma_f32_32x32x16_bf16 v[0:15], v[76:79], v[98:101], v[0:15]
	ds_read_b128 v[98:101], v96 offset:34816
	s_cmp_eq_u32 s5, 34
	s_cbranch_scc1 .Lmy_exit
	s_mov_b32 s2, s5
	s_branch .LBB0_784
